# v53 + in-proj epilogue: vmcnt(0) before the bias loads relaxed to vmcnt(8) so the next unit's prefetched LDS-DMA tiles stay in flight during the epilogue
# baseline (speedup 1.0000x reference)
; #define PG8_BAR __builtin_amdgcn_s_barrier()
; template <class Epi>
; __device__ __forceinline__ void gemm_phase(LAS unsigned char* lds, const Gemm g, const StaticOrder& S, const Epi& E, const int tid) {
;     ...
;         if (wr == 0) PG8_BAR;
;         if (has_next) E.pre(nxt.pm, tid, pf);
.LBB0_271:
	v_cndmask_b32_e64 v150, 0, 1, s[42:43]
	v_cmp_ne_u32_e64 s[40:41], 1, v150
	s_andn2_b64 vcc, exec, s[42:43]
	s_movk_i32 s33, 0x1800
	s_cbranch_vccnz .LBB0_273
	s_lshl_b64 s[8:9], s[86:87], 14
	s_waitcnt vmcnt(8)
	v_lshl_add_u64 v[4:5], v[144:145], 0, s[8:9]
	global_load_dwordx4 v[0:3], v[4:5], off offset:16
	s_nop 0
	global_load_dwordx4 v[4:7], v[4:5], off

; #define PG8_BAR __builtin_amdgcn_s_barrier()
; template <class Epi>
; __device__ __forceinline__ void gemm_phase(LAS unsigned char* lds, const Gemm g, const StaticOrder& S, const Epi& E, const int tid) {
;     ...
;         if (wr == 0) PG8_BAR;
;         if (has_next) E.pre(nxt.pm, tid, pf);
.LBB0_359:
	v_cndmask_b32_e64 v150, 0, 1, s[40:41]
	v_readlane_b32 s96, v255, 45
	v_cmp_ne_u32_e64 s[42:43], 1, v150
	s_andn2_b64 vcc, exec, s[40:41]
	v_readlane_b32 s97, v255, 46
	s_cbranch_vccnz .LBB0_361
	s_lshl_b64 s[8:9], s[84:85], 14
	s_waitcnt vmcnt(8)
	v_lshl_add_u64 v[4:5], v[144:145], 0, s[8:9]
	global_load_dwordx4 v[0:3], v[4:5], off offset:16
	s_nop 0
	global_load_dwordx4 v[4:7], v[4:5], off
